# H3 output stage: the 8 norm-gain loads issued up front into dead registers with counted in-order waits (was 8 serial load+vmcnt(0) round trips)
# speedup vs baseline: 1.0027x; 1.0027x over previous
; __device__ __forceinline__ unsigned cvt_pk_bf16_c(float lo, float hi) { const f32x2_t v = {lo, hi}; return __builtin_bit_cast(unsigned, __builtin_convertvector(v, bf16x2_t)); }
; __device__ __forceinline__ float bperm(float v, int src_lane) { return __int_as_float(__builtin_amdgcn_ds_bpermute(src_lane << 2, __float_as_int(v))); }
; __host__ __device__ __forceinline__ size_t xs_off(int row, int col) { return (size_t)(row >> 8) * (256 * D) + (size_t)(col >> 6) * (256 * 64) + (size_t)((row & 255) * 64 + (col & 63)); }
; __device__ __forceinline__ void hgrn_h3(LAS unsigned char* lds, const bf16_t* Q, const _Float16* LF, const bf16_t* V, const bf16_t* SG, const bf16_t* SP, const float* gn, bf16_t* YAB, int cid, int G, int tid) {
;     ...
;             float ss = 0.f;
; #pragma unroll
;             for (int vt = 0; vt < 8; ++vt) ss += (acc[vt].x * acc[vt].x + acc[vt].y * acc[vt].y) + (acc[vt].z * acc[vt].z + acc[vt].w * acc[vt].w);
;             ss += bperm(ss, lane ^ 16); ss += bperm(ss, lane ^ 32);
;             const float rstd = rsqrtf(ss * (1.f / 128.f) + EPS);
; #pragma unroll
;             for (int j = 0; j < 4; ++j) {
;                 const auto g0 = __builtin_amdgcn_permlane16_swap(sgw[j].x, sgw[j].z, false, false); const auto g1 = __builtin_amdgcn_permlane16_swap(sgw[j].y, sgw[j].w, false, false);
;                 u32x2 sg2[2]; sg2[0].x = g0[0]; sg2[0].y = g1[0]; sg2[1].x = g0[1]; sg2[1].y = g1[1];
;                 u32x2 o2[2];
; #pragma unroll
;                 for (int q = 0; q < 2; ++q) { const int vt = 2 * j + q, vc = 16 * vt + 4 * fq; const f32x4 g4 = *(const f32x4*)(gn + vc);
;                     const float s0 = __uint_as_float(sg2[q].x << 16), s1 = __uint_as_float(sg2[q].x & 0xffff0000u), s2 = __uint_as_float(sg2[q].y << 16), s3 = __uint_as_float(sg2[q].y & 0xffff0000u);
;                     o2[q].x = cvt_pk_bf16_c(acc[vt].x * rstd * g4.x * s0, acc[vt].y * rstd * g4.y * s1); o2[q].y = cvt_pk_bf16_c(acc[vt].z * rstd * g4.z * s2, acc[vt].w * rstd * g4.w * s3); }
;                 const auto r0 = __builtin_amdgcn_permlane16_swap(o2[0].x, o2[1].x, false, false); const auto r1 = __builtin_amdgcn_permlane16_swap(o2[0].y, o2[1].y, false, false);
;                 u32x4 wv; wv.x = r0[0]; wv.y = r1[0]; wv.z = r0[1]; wv.w = r1[1];
;                 *(u32x4*)(YAB + xs_off((int)grow, h * 128 + 32 * j + vsw)) = wv; }
.LBB0_1027:
	s_nop 3
	v_mov_b32_e32 v118, v165
	v_mov_b32_e32 v119, v169
	v_mov_b32_e32 v116, v164
	v_mov_b32_e32 v117, v168
	v_pk_mul_f32 v[118:119], v[118:119], v[118:119]
	v_mov_b32_e32 v128, v167
	v_mov_b32_e32 v129, v171
	v_pk_fma_f32 v[116:117], v[116:117], v[116:117], v[118:119]
	v_mov_b32_e32 v118, v166
	v_mov_b32_e32 v119, v170
	v_pk_mul_f32 v[128:129], v[128:129], v[128:129]
	v_mul_f32_e32 v0, v156, v156
	v_pk_fma_f32 v[118:119], v[118:119], v[118:119], v[128:129]
	v_pk_mul_f32 v[128:129], v[160:161], v[160:161]
	v_pk_add_f32 v[116:117], v[116:117], v[118:119]
	v_pk_mul_f32 v[118:119], v[162:163], v[162:163]
	v_pk_add_f32 v[116:117], v[116:117], v[116:117] op_sel_hi:[0,1]
	v_pk_mov_b32 v[130:131], v[128:129], v[118:119] op_sel:[1,0]
	v_mov_b32_e32 v129, v119
	v_pk_add_f32 v[118:119], v[130:131], v[128:129]
	v_pk_fma_f32 v[128:129], v[156:157], v[156:157], v[0:1] op_sel_hi:[1,1,0]
	v_mul_f32_e32 v0, v158, v158
	v_pk_add_f32 v[118:119], v[118:119], v[118:119] op_sel_hi:[0,1]
	v_pk_fma_f32 v[130:131], v[158:159], v[158:159], v[0:1] op_sel_hi:[1,1,0]
	v_mul_f32_e32 v128, v152, v152
	v_mul_f32_e32 v130, v153, v153
	v_mul_f32_e32 v118, v154, v154
	v_mul_f32_e32 v116, v155, v155
	v_pk_add_f32 v[128:129], v[128:129], v[130:131]
	v_pk_add_f32 v[116:117], v[118:119], v[116:117]
	v_pk_mul_f32 v[118:119], v[146:147], v[146:147]
	v_pk_add_f32 v[116:117], v[128:129], v[116:117]
	v_pk_mul_f32 v[128:129], v[144:145], v[144:145]
	v_mul_f32_e32 v0, v140, v140
	v_pk_mov_b32 v[130:131], v[128:129], v[118:119] op_sel:[1,0]
	v_mov_b32_e32 v129, v119
	v_pk_add_f32 v[118:119], v[130:131], v[128:129]
	v_pk_fma_f32 v[128:129], v[140:141], v[140:141], v[0:1] op_sel_hi:[1,1,0]
	v_mul_f32_e32 v0, v142, v142
	v_pk_add_f32 v[116:117], v[116:117], v[116:117] op_sel_hi:[0,1]
	v_pk_add_f32 v[118:119], v[118:119], v[118:119] op_sel_hi:[0,1]
	v_pk_fma_f32 v[130:131], v[142:143], v[142:143], v[0:1] op_sel_hi:[1,1,0]
	v_mul_f32_e32 v128, v124, v124
	v_mul_f32_e32 v130, v125, v125
	v_mul_f32_e32 v118, v126, v126
	v_mul_f32_e32 v116, v127, v127
	v_pk_add_f32 v[128:129], v[128:129], v[130:131]
	v_pk_add_f32 v[116:117], v[118:119], v[116:117]
	v_lshlrev_b32_e32 v3, 2, v223
	v_pk_add_f32 v[116:117], v[128:129], v[116:117]
	v_ashrrev_i32_e32 v201, 31, v200
	v_add_f32_e32 v0, v116, v117
	v_xor_b32_e32 v116, 64, v3
	ds_bpermute_b32 v116, v116, v0
	v_xor_b32_e32 v3, 0x80, v3
	s_waitcnt vmcnt(3)
	v_mov_b32_e32 v118, v151
	s_lshl_b32 s6, s68, 7
	v_add_u32_e32 v175, s6, v2
	s_waitcnt lgkmcnt(0)
	v_add_f32_e32 v0, v0, v116
	ds_bpermute_b32 v3, v3, v0
	v_ashrrev_i32_e32 v116, 8, v216
	v_ashrrev_i32_e32 v117, 31, v116
	v_lshlrev_b64 v[116:117], 20, v[116:117]
	v_lshl_add_u64 v[172:173], s[18:19], 0, v[116:117]
	s_waitcnt lgkmcnt(0)
	v_add_f32_e32 v0, v0, v3
	v_fmamk_f32 v0, v0, 0x3c000000, v240
	v_cmp_gt_f32_e32 vcc, s3, v0
	v_mul_f32_e32 v3, 0x4b800000, v0
	v_permlane16_swap_b32_e32 v149, v118
	v_cndmask_b32_e32 v0, v0, v3, vcc
	v_rsq_f32_e32 v0, v0
	s_nop 0
	v_mul_f32_e32 v3, 0x45800000, v0
	v_cndmask_b32_e32 v174, v0, v3, vcc
	v_lshlrev_b32_e32 v0, 6, v216
	v_and_b32_e32 v3, 0x3fc0, v0
	v_mov_b32_e32 v0, v150
	v_lshl_add_u64 v[150:151], v[200:201], 2, s[16:17]
	global_load_dwordx4 v[128:131], v[150:151], off
	global_load_dwordx4 v[180:183], v[150:151], off offset:64
	global_load_dwordx4 v[184:187], v[150:151], off offset:128
	global_load_dwordx4 v[188:191], v[150:151], off offset:192
	global_load_dwordx4 v[194:197], v[150:151], off offset:256
	global_load_dwordx4 v[202:205], v[150:151], off offset:320
	global_load_dwordx4 v[224:227], v[150:151], off offset:384
	global_load_dwordx4 v[244:247], v[150:151], off offset:448
	v_permlane16_swap_b32_e32 v148, v0
	v_pk_mul_f32 v[168:169], v[168:169], v[174:175] op_sel_hi:[1,0]
	v_lshlrev_b32_e32 v116, 16, v148
	v_and_b32_e32 v117, 0xffff0000, v148
	v_lshlrev_b32_e32 v148, 16, v149
	v_and_b32_e32 v149, 0xffff0000, v149
	v_pk_mul_f32 v[124:125], v[124:125], v[174:175] op_sel_hi:[1,0]
	s_waitcnt vmcnt(7)
	v_pk_mul_f32 v[128:129], v[128:129], v[168:169]
	s_nop 0
	v_pk_mul_f32 v[116:117], v[128:129], v[116:117]
	v_pk_mul_f32 v[128:129], v[170:171], v[174:175] op_sel_hi:[1,0]
	v_cvt_pk_bf16_f32 v116, v116, v117
	v_pk_mul_f32 v[128:129], v[130:131], v[128:129]
	v_lshlrev_b32_e32 v168, 16, v118
	v_pk_mul_f32 v[128:129], v[128:129], v[148:149]
	v_and_b32_e32 v169, 0xffff0000, v118
	v_cvt_pk_bf16_f32 v117, v128, v129
	v_pk_mul_f32 v[118:119], v[164:165], v[174:175] op_sel_hi:[1,0]
	v_lshlrev_b32_e32 v148, 16, v0
	v_and_b32_e32 v149, 0xffff0000, v0
	v_and_or_b32 v0, v2, 60, v3
	v_lshlrev_b32_e32 v0, 1, v0
	v_mov_b32_e32 v2, v138
	v_mov_b32_e32 v138, v139
	s_nop 0
	v_permlane16_swap_b32_e32 v136, v2
	v_permlane16_swap_b32_e32 v137, v138
	s_waitcnt vmcnt(6)
; __device__ __forceinline__ unsigned cvt_pk_bf16_c(float lo, float hi) { const f32x2_t v = {lo, hi}; return __builtin_bit_cast(unsigned, __builtin_convertvector(v, bf16x2_t)); }
; __host__ __device__ __forceinline__ size_t xs_off(int row, int col) { return (size_t)(row >> 8) * (256 * D) + (size_t)(col >> 6) * (256 * 64) + (size_t)((row & 255) * 64 + (col & 63)); }
; __device__ __forceinline__ void hgrn_h3(LAS unsigned char* lds, const bf16_t* Q, const _Float16* LF, const bf16_t* V, const bf16_t* SG, const bf16_t* SP, const float* gn, bf16_t* YAB, int cid, int G, int tid) {
;     ...
;             for (int j = 0; j < 4; ++j) {
;                 const auto g0 = __builtin_amdgcn_permlane16_swap(sgw[j].x, sgw[j].z, false, false); const auto g1 = __builtin_amdgcn_permlane16_swap(sgw[j].y, sgw[j].w, false, false);
;                 u32x2 sg2[2]; sg2[0].x = g0[0]; sg2[0].y = g1[0]; sg2[1].x = g0[1]; sg2[1].y = g1[1];
;                 u32x2 o2[2];
; #pragma unroll
;                 for (int q = 0; q < 2; ++q) { const int vt = 2 * j + q, vc = 16 * vt + 4 * fq; const f32x4 g4 = *(const f32x4*)(gn + vc);
;                     const float s0 = __uint_as_float(sg2[q].x << 16), s1 = __uint_as_float(sg2[q].x & 0xffff0000u), s2 = __uint_as_float(sg2[q].y << 16), s3 = __uint_as_float(sg2[q].y & 0xffff0000u);
;                     o2[q].x = cvt_pk_bf16_c(acc[vt].x * rstd * g4.x * s0, acc[vt].y * rstd * g4.y * s1); o2[q].y = cvt_pk_bf16_c(acc[vt].z * rstd * g4.z * s2, acc[vt].w * rstd * g4.w * s3); }
;                 const auto r0 = __builtin_amdgcn_permlane16_swap(o2[0].x, o2[1].x, false, false); const auto r1 = __builtin_amdgcn_permlane16_swap(o2[0].y, o2[1].y, false, false);
;                 u32x4 wv; wv.x = r0[0]; wv.y = r1[0]; wv.z = r0[1]; wv.w = r1[1];
;                 *(u32x4*)(YAB + xs_off((int)grow, h * 128 + 32 * j + vsw)) = wv; }
	v_pk_mul_f32 v[118:119], v[180:181], v[118:119]
	v_pk_mul_f32 v[128:129], v[166:167], v[174:175] op_sel_hi:[1,0]
	v_pk_mul_f32 v[118:119], v[118:119], v[148:149]
	v_pk_mul_f32 v[128:129], v[182:183], v[128:129]
	v_cvt_pk_bf16_f32 v118, v118, v119
	v_pk_mul_f32 v[128:129], v[128:129], v[168:169]
	s_nop 0
	v_permlane16_swap_b32_e32 v116, v118
	v_cvt_pk_bf16_f32 v119, v128, v129
	v_ashrrev_i32_e32 v128, 6, v175
	v_ashrrev_i32_e32 v129, 31, v128
	v_lshlrev_b64 v[128:129], 15, v[128:129]
	v_lshl_add_u64 v[128:129], v[172:173], 0, v[128:129]
	v_permlane16_swap_b32_e32 v117, v119
	v_lshl_add_u64 v[128:129], v[128:129], 0, v[0:1]
	global_store_dwordx4 v[128:129], v[116:119], off
	v_lshlrev_b32_e32 v128, 16, v136
	v_and_b32_e32 v129, 0xffff0000, v136
	v_lshlrev_b32_e32 v130, 16, v137
	v_and_b32_e32 v131, 0xffff0000, v137
	v_pk_mul_f32 v[136:137], v[160:161], v[174:175] op_sel_hi:[1,0]
	s_waitcnt vmcnt(6)
	v_pk_mul_f32 v[116:117], v[184:185], v[136:137]
	s_nop 0
	v_pk_mul_f32 v[116:117], v[116:117], v[128:129]
	v_pk_mul_f32 v[128:129], v[162:163], v[174:175] op_sel_hi:[1,0]
	v_lshlrev_b32_e32 v136, 16, v138
	v_pk_mul_f32 v[118:119], v[186:187], v[128:129]
	v_and_b32_e32 v137, 0xffff0000, v138
	v_pk_mul_f32 v[118:119], v[118:119], v[130:131]
	v_pk_mul_f32 v[138:139], v[156:157], v[174:175] op_sel_hi:[1,0]
	v_cvt_pk_bf16_f32 v116, v116, v117
	v_cvt_pk_bf16_f32 v117, v118, v119
	v_lshlrev_b32_e32 v118, 16, v2
	v_and_b32_e32 v119, 0xffff0000, v2
	v_add_u32_e32 v2, 32, v175
	s_waitcnt vmcnt(5)
	v_pk_mul_f32 v[128:129], v[188:189], v[138:139]
	s_nop 0
	v_pk_mul_f32 v[118:119], v[128:129], v[118:119]
	v_pk_mul_f32 v[128:129], v[158:159], v[174:175] op_sel_hi:[1,0]
	v_cvt_pk_bf16_f32 v118, v118, v119
	v_pk_mul_f32 v[128:129], v[190:191], v[128:129]
	v_mov_b32_e32 v131, v1
	v_pk_mul_f32 v[128:129], v[128:129], v[136:137]
	v_permlane16_swap_b32_e32 v116, v118
	v_cvt_pk_bf16_f32 v119, v128, v129
	v_ashrrev_i32_e32 v128, 6, v2
	v_ashrrev_i32_e32 v129, 31, v128
	v_and_or_b32 v2, v2, 60, v3
	v_lshlrev_b64 v[128:129], 15, v[128:129]
	v_lshl_add_u64 v[128:129], v[172:173], 0, v[128:129]
	v_lshlrev_b32_e32 v130, 1, v2
	v_permlane16_swap_b32_e32 v117, v119
	v_lshl_add_u64 v[128:129], v[128:129], 0, v[130:131]
	global_store_dwordx4 v[128:129], v[116:119], off
	v_mov_b32_e32 v2, v134
	v_mov_b32_e32 v134, v135
	s_nop 0
	v_permlane16_swap_b32_e32 v132, v2
	v_permlane16_swap_b32_e32 v133, v134
	v_lshlrev_b32_e32 v128, 16, v132
	v_and_b32_e32 v129, 0xffff0000, v132
	v_lshlrev_b32_e32 v130, 16, v133
	v_and_b32_e32 v131, 0xffff0000, v133
	v_pk_mul_f32 v[132:133], v[152:153], v[174:175] op_sel_hi:[1,0]
	s_waitcnt vmcnt(5)
	v_pk_mul_f32 v[116:117], v[194:195], v[132:133]
	s_nop 0
	v_pk_mul_f32 v[116:117], v[116:117], v[128:129]
	v_pk_mul_f32 v[128:129], v[154:155], v[174:175] op_sel_hi:[1,0]
	v_lshlrev_b32_e32 v132, 16, v134
	v_pk_mul_f32 v[118:119], v[196:197], v[128:129]
	v_and_b32_e32 v133, 0xffff0000, v134
	v_pk_mul_f32 v[118:119], v[118:119], v[130:131]
	v_pk_mul_f32 v[134:135], v[144:145], v[174:175] op_sel_hi:[1,0]
	v_cvt_pk_bf16_f32 v116, v116, v117
	v_cvt_pk_bf16_f32 v117, v118, v119
	v_lshlrev_b32_e32 v118, 16, v2
	v_and_b32_e32 v119, 0xffff0000, v2
	v_add_u32_e32 v2, 64, v175
	s_waitcnt vmcnt(4)
	v_pk_mul_f32 v[128:129], v[202:203], v[134:135]
	s_nop 0
	v_pk_mul_f32 v[118:119], v[128:129], v[118:119]
	v_pk_mul_f32 v[128:129], v[146:147], v[174:175] op_sel_hi:[1,0]
	v_cvt_pk_bf16_f32 v118, v118, v119
	v_pk_mul_f32 v[128:129], v[204:205], v[128:129]
	s_nop 0
	v_permlane16_swap_b32_e32 v116, v118
	v_pk_mul_f32 v[128:129], v[128:129], v[132:133]
	s_nop 0
	v_cvt_pk_bf16_f32 v119, v128, v129
	v_ashrrev_i32_e32 v128, 6, v2
	v_ashrrev_i32_e32 v129, 31, v128
	v_lshlrev_b64 v[128:129], 15, v[128:129]
	v_lshl_add_u64 v[128:129], v[172:173], 0, v[128:129]
	v_permlane16_swap_b32_e32 v117, v119
	v_lshl_add_u64 v[128:129], v[128:129], 0, v[0:1]
	global_store_dwordx4 v[128:129], v[116:119], off
	v_mov_b32_e32 v0, v122
	s_nop 1
	v_permlane16_swap_b32_e32 v120, v0
	v_pk_mul_f32 v[128:129], v[140:141], v[174:175] op_sel_hi:[1,0]
	v_mov_b32_e32 v2, v123
	v_lshlrev_b32_e32 v122, 16, v120
	v_and_b32_e32 v123, 0xffff0000, v120
	v_permlane16_swap_b32_e32 v121, v2
	v_lshlrev_b32_e32 v120, 16, v121
	v_and_b32_e32 v121, 0xffff0000, v121
	s_waitcnt vmcnt(4)
	v_pk_mul_f32 v[116:117], v[128:129], v[224:225]
	s_nop 0
	v_pk_mul_f32 v[116:117], v[116:117], v[122:123]
	v_pk_mul_f32 v[122:123], v[142:143], v[174:175] op_sel_hi:[1,0]
	v_cvt_pk_bf16_f32 v116, v116, v117
	v_pk_mul_f32 v[118:119], v[122:123], v[226:227]
	v_lshlrev_b32_e32 v122, 16, v0
	v_pk_mul_f32 v[118:119], v[118:119], v[120:121]
	v_and_b32_e32 v123, 0xffff0000, v0
	v_cvt_pk_bf16_f32 v117, v118, v119
	v_lshlrev_b32_e32 v128, 16, v2
	v_and_b32_e32 v129, 0xffff0000, v2
	v_add_u32_e32 v0, 0x60, v175
	s_waitcnt vmcnt(3)
	v_pk_mul_f32 v[118:119], v[124:125], v[244:245]
	s_nop 0
	v_pk_mul_f32 v[118:119], v[118:119], v[122:123]
	v_pk_mul_f32 v[122:123], v[126:127], v[174:175] op_sel_hi:[1,0]
	v_cvt_pk_bf16_f32 v118, v118, v119
	v_pk_mul_f32 v[120:121], v[122:123], v[246:247]
	s_nop 0
	v_permlane16_swap_b32_e32 v116, v118
	v_pk_mul_f32 v[120:121], v[120:121], v[128:129]
	s_nop 0
	v_cvt_pk_bf16_f32 v119, v120, v121
	v_ashrrev_i32_e32 v120, 6, v0
	v_ashrrev_i32_e32 v121, 31, v120
	v_and_or_b32 v0, v0, 60, v3
	v_lshlrev_b64 v[2:3], 15, v[120:121]
	v_lshl_add_u64 v[2:3], v[172:173], 0, v[2:3]
	v_lshlrev_b32_e32 v0, 1, v0
	v_permlane16_swap_b32_e32 v117, v119
	v_lshl_add_u64 v[2:3], v[2:3], 0, v[0:1]
	global_store_dwordx4 v[2:3], v[116:119], off
